# P7 next-layer weight conversion (w_glu, w_branch x3, w_out) hand-batched into one 5-item round with the 16x4 wave mapping
# speedup vs baseline: 1.0142x; 1.0058x over previous
.LBB0_950:
	s_or_b64 exec, exec, s[6:7]
	v_readlane_b32 s0, v253, 4
	v_readlane_b32 s1, v253, 5
	s_andn2_b64 vcc, exec, s[0:1]
	s_cbranch_vccnz .LBB0_982
	v_readlane_b32 s20, v253, 48
	v_readlane_b32 s0, v253, 2
	v_readlane_b32 s1, v253, 3
	v_readlane_b32 s2, v254, 1
	v_readlane_b32 s3, v254, 2
	v_readlane_b32 s4, v253, 36
	v_readlane_b32 s5, v253, 37
	v_readlane_b32 s6, v253, 38
	v_readlane_b32 s7, v253, 39
	v_readlane_b32 s8, v253, 40
	v_readlane_b32 s9, v253, 41
	v_readlane_b32 s22, v253, 42
	v_readlane_b32 s23, v253, 43
	v_add_u32_e32 v29, s20, v83
	v_readlane_b32 s20, v255, 29
	s_nop 1
	s_lshl_b32 s21, s20, 20
	s_add_u32 s2, s2, s21
	s_addc_u32 s3, s3, 0
	s_lshl_b32 s21, s20, 21
	s_add_u32 s4, s4, s21
	s_addc_u32 s5, s5, 0
	s_add_u32 s6, s6, s21
	s_addc_u32 s7, s7, 0
	s_add_u32 s8, s8, s21
	s_addc_u32 s9, s9, 0
	s_lshl_b32 s21, s20, 22
	s_add_u32 s22, s22, s21
	s_addc_u32 s23, s23, 0
	s_mov_b64 s[20:21], exec
	v_mov_b32_e32 v40, v29
	v_cmp_gt_u32_e32 vcc, 0x20000, v40
	s_mov_b64 s[10:11], vcc
	v_lshrrev_b32_e32 v41, 6, v40
	v_lshrrev_b32_e32 v42, 12, v40
	v_lshlrev_b32_e32 v41, 6, v42
	v_lshrrev_b32_e32 v44, 6, v40
	v_sub_u32_e32 v41, v44, v41
	v_bfe_u32 v44, v40, 4, 2
	v_lshl_add_u32 v44, v42, 2, v44
	v_and_b32_e32 v42, 15, v40
	v_lshl_add_u32 v42, v41, 4, v42
	v_mov_b32_e32 v41, v44
	v_mul_u32_u24_e32 v43, 0x8000, v41
	v_lshl_add_u32 v43, v42, 2, v43
	v_lshlrev_b32_e32 v24, 11, v42
	v_lshl_add_u32 v24, v41, 4, v24
	v_add_u32_e32 v24, 0x1700000, v24
	s_mov_b64 exec, s[10:11]
	global_load_dword v0, v43, s[22:23]
	v_add_u32_e32 v43, 0x1000, v43
	global_load_dword v1, v43, s[22:23]
	v_add_u32_e32 v43, 0x1000, v43
	global_load_dword v2, v43, s[22:23]
	v_add_u32_e32 v43, 0x1000, v43
	global_load_dword v3, v43, s[22:23]
	v_add_u32_e32 v43, 0x1000, v43
	global_load_dword v4, v43, s[22:23]
	v_add_u32_e32 v43, 0x1000, v43
	global_load_dword v5, v43, s[22:23]
	v_add_u32_e32 v43, 0x1000, v43
	global_load_dword v6, v43, s[22:23]
	v_add_u32_e32 v43, 0x1000, v43
	global_load_dword v7, v43, s[22:23]
	s_mov_b64 exec, s[20:21]
	v_mov_b32_e32 v40, v29
	v_cmp_gt_u32_e32 vcc, 0x10000, v40
	s_mov_b64 s[12:13], vcc
	v_lshrrev_b32_e32 v41, 6, v40
	v_lshrrev_b32_e32 v42, 12, v40
	v_lshlrev_b32_e32 v41, 6, v42
	v_lshrrev_b32_e32 v44, 6, v40
	v_sub_u32_e32 v41, v44, v41
	v_bfe_u32 v44, v40, 4, 2
	v_lshl_add_u32 v44, v42, 2, v44
	v_and_b32_e32 v42, 15, v40
	v_lshl_add_u32 v42, v41, 4, v42
	v_mov_b32_e32 v41, v44
	v_mul_u32_u24_e32 v43, 0x8000, v41
	v_lshl_add_u32 v43, v42, 2, v43
	v_lshlrev_b32_e32 v25, 10, v42
	v_lshl_add_u32 v25, v41, 4, v25
	v_add_u32_e32 v25, 0x1400000, v25
	s_mov_b64 exec, s[12:13]
	global_load_dword v8, v43, s[4:5]
	v_add_u32_e32 v43, 0x1000, v43
	global_load_dword v9, v43, s[4:5]
	v_add_u32_e32 v43, 0x1000, v43
	global_load_dword v10, v43, s[4:5]
	v_add_u32_e32 v43, 0x1000, v43
	global_load_dword v11, v43, s[4:5]
	v_add_u32_e32 v43, 0x1000, v43
	global_load_dword v12, v43, s[4:5]
	v_add_u32_e32 v43, 0x1000, v43
	global_load_dword v13, v43, s[4:5]
	v_add_u32_e32 v43, 0x1000, v43
	global_load_dword v14, v43, s[4:5]
	v_add_u32_e32 v43, 0x1000, v43
	global_load_dword v15, v43, s[4:5]
	s_mov_b64 exec, s[20:21]
	v_mov_b32_e32 v40, v29
	v_cmp_gt_u32_e32 vcc, 0x10000, v40
	s_mov_b64 s[14:15], vcc
	v_lshrrev_b32_e32 v41, 6, v40
	v_lshrrev_b32_e32 v42, 12, v40
	v_lshlrev_b32_e32 v41, 6, v42
	v_lshrrev_b32_e32 v44, 6, v40
	v_sub_u32_e32 v41, v44, v41
	v_bfe_u32 v44, v40, 4, 2
	v_lshl_add_u32 v44, v42, 2, v44
	v_and_b32_e32 v42, 15, v40
	v_lshl_add_u32 v42, v41, 4, v42
	v_mov_b32_e32 v41, v44
	v_mul_u32_u24_e32 v43, 0x8000, v41
	v_lshl_add_u32 v43, v42, 2, v43
	v_lshlrev_b32_e32 v26, 10, v42
	v_lshl_add_u32 v26, v41, 4, v26
	v_add_u32_e32 v26, 0x1500000, v26
	s_mov_b64 exec, s[14:15]
	global_load_dword v16, v43, s[6:7]
	v_add_u32_e32 v43, 0x1000, v43
	global_load_dword v17, v43, s[6:7]
	v_add_u32_e32 v43, 0x1000, v43
	global_load_dword v18, v43, s[6:7]
	v_add_u32_e32 v43, 0x1000, v43
	global_load_dword v19, v43, s[6:7]
	v_add_u32_e32 v43, 0x1000, v43
	global_load_dword v20, v43, s[6:7]
	v_add_u32_e32 v43, 0x1000, v43
	global_load_dword v21, v43, s[6:7]
	v_add_u32_e32 v43, 0x1000, v43
	global_load_dword v22, v43, s[6:7]
	v_add_u32_e32 v43, 0x1000, v43
	global_load_dword v23, v43, s[6:7]
	s_mov_b64 exec, s[20:21]
	v_mov_b32_e32 v40, v29
	v_cmp_gt_u32_e32 vcc, 0x10000, v40
	s_mov_b64 s[16:17], vcc
	v_lshrrev_b32_e32 v41, 6, v40
	v_lshrrev_b32_e32 v42, 12, v40
	v_lshlrev_b32_e32 v41, 6, v42
	v_lshrrev_b32_e32 v44, 6, v40
	v_sub_u32_e32 v41, v44, v41
	v_bfe_u32 v44, v40, 4, 2
	v_lshl_add_u32 v44, v42, 2, v44
	v_and_b32_e32 v42, 15, v40
	v_lshl_add_u32 v42, v41, 4, v42
	v_mov_b32_e32 v41, v44
	v_mul_u32_u24_e32 v43, 0x8000, v41
	v_lshl_add_u32 v43, v42, 2, v43
	v_lshlrev_b32_e32 v27, 10, v42
	v_lshl_add_u32 v27, v41, 4, v27
	v_add_u32_e32 v27, 0x1600000, v27
	s_mov_b64 exec, s[16:17]
	global_load_dword v32, v43, s[8:9]
	v_add_u32_e32 v43, 0x1000, v43
	global_load_dword v33, v43, s[8:9]
	v_add_u32_e32 v43, 0x1000, v43
	global_load_dword v34, v43, s[8:9]
	v_add_u32_e32 v43, 0x1000, v43
	global_load_dword v35, v43, s[8:9]
	v_add_u32_e32 v43, 0x1000, v43
	global_load_dword v36, v43, s[8:9]
	v_add_u32_e32 v43, 0x1000, v43
	global_load_dword v37, v43, s[8:9]
	v_add_u32_e32 v43, 0x1000, v43
	global_load_dword v38, v43, s[8:9]
	v_add_u32_e32 v43, 0x1000, v43
	global_load_dword v39, v43, s[8:9]
	s_mov_b64 exec, s[20:21]
	v_mov_b32_e32 v40, v29
	v_cmp_gt_u32_e32 vcc, 0x8000, v40
	s_mov_b64 s[18:19], vcc
	v_lshrrev_b32_e32 v41, 6, v40
	v_lshrrev_b32_e32 v42, 11, v40
	v_lshlrev_b32_e32 v41, 5, v42
	v_lshrrev_b32_e32 v44, 6, v40
	v_sub_u32_e32 v41, v44, v41
	v_bfe_u32 v44, v40, 4, 2
	v_lshl_add_u32 v44, v42, 2, v44
	v_and_b32_e32 v42, 15, v40
	v_lshl_add_u32 v42, v41, 4, v42
	v_mov_b32_e32 v41, v44
	v_mul_u32_u24_e32 v43, 0x4000, v41
	v_lshl_add_u32 v43, v42, 2, v43
	v_lshlrev_b32_e32 v28, 10, v42
	v_lshl_add_u32 v28, v41, 4, v28
	v_add_u32_e32 v28, 0x1300000, v28
	s_mov_b64 exec, s[18:19]
	global_load_dword v48, v43, s[2:3]
	v_add_u32_e32 v43, 0x800, v43
	global_load_dword v49, v43, s[2:3]
	v_add_u32_e32 v43, 0x800, v43
	global_load_dword v50, v43, s[2:3]
	v_add_u32_e32 v43, 0x800, v43
	global_load_dword v51, v43, s[2:3]
	v_add_u32_e32 v43, 0x800, v43
	global_load_dword v52, v43, s[2:3]
	v_add_u32_e32 v43, 0x800, v43
	global_load_dword v53, v43, s[2:3]
	v_add_u32_e32 v43, 0x800, v43
	global_load_dword v54, v43, s[2:3]
	v_add_u32_e32 v43, 0x800, v43
	global_load_dword v55, v43, s[2:3]
	s_mov_b64 exec, s[20:21]
	s_waitcnt vmcnt(0)
	s_mov_b64 exec, s[10:11]
	v_cvt_pk_bf16_f32 v0, v0, v1
	v_cvt_pk_bf16_f32 v1, v2, v3
	v_cvt_pk_bf16_f32 v2, v4, v5
	v_cvt_pk_bf16_f32 v3, v6, v7
	global_store_dwordx4 v24, v[0:3], s[0:1]
	s_mov_b64 exec, s[20:21]
	s_mov_b64 exec, s[12:13]
	v_cvt_pk_bf16_f32 v8, v8, v9
	v_cvt_pk_bf16_f32 v9, v10, v11
	v_cvt_pk_bf16_f32 v10, v12, v13
	v_cvt_pk_bf16_f32 v11, v14, v15
	global_store_dwordx4 v25, v[8:11], s[0:1]
	s_mov_b64 exec, s[20:21]
	s_mov_b64 exec, s[14:15]
	v_cvt_pk_bf16_f32 v16, v16, v17
	v_cvt_pk_bf16_f32 v17, v18, v19
	v_cvt_pk_bf16_f32 v18, v20, v21
	v_cvt_pk_bf16_f32 v19, v22, v23
	global_store_dwordx4 v26, v[16:19], s[0:1]
	s_mov_b64 exec, s[20:21]
	s_mov_b64 exec, s[16:17]
	v_cvt_pk_bf16_f32 v32, v32, v33
	v_cvt_pk_bf16_f32 v33, v34, v35
	v_cvt_pk_bf16_f32 v34, v36, v37
	v_cvt_pk_bf16_f32 v35, v38, v39
	global_store_dwordx4 v27, v[32:35], s[0:1]
	s_mov_b64 exec, s[20:21]
	s_mov_b64 exec, s[18:19]
	v_cvt_pk_bf16_f32 v48, v48, v49
	v_cvt_pk_bf16_f32 v49, v50, v51
	v_cvt_pk_bf16_f32 v50, v52, v53
	v_cvt_pk_bf16_f32 v51, v54, v55
	global_store_dwordx4 v28, v[48:51], s[0:1]
	s_mov_b64 exec, s[20:21]
